# grid barrier: last arriver of each XCD issues its buffer_inv after the release write-back and top-level arrival atomic instead of before the write-back
# speedup vs baseline: 1.0047x; 1.0010x over previous
; DI unsigned xb_ld(unsigned* p) { return __hip_atomic_load(p, __ATOMIC_RELAXED, __HIP_MEMORY_SCOPE_AGENT); }
; DI unsigned xb_add(unsigned* p, unsigned v) { return __hip_atomic_fetch_add(p, v, __ATOMIC_RELAXED, __HIP_MEMORY_SCOPE_AGENT); }
; #define XB_SPIN(cond, bar) do { unsigned _sp = 0; while (cond) { __builtin_amdgcn_s_sleep(1); \
;     if ((++_sp & 255u) == 0u) { if (xb_ld(&(bar)[XB_TMO])) break; if (_sp > XB_SPIN_CAP) { atomicAdd(&(bar)[XB_TMO], 1u); break; } } } } while (0)
; DI void xcd_barrier(const XcdBarrier& b) {
;     ...
;     const unsigned old = xb_add(&bar[XB_XSUB(b.x)], 1u);
;     const unsigned gen = old / nloc;
;     if (old + 1u == (gen + 1u) * nloc) {
;       __builtin_amdgcn_fence(__ATOMIC_RELEASE, "agent");
;       asm volatile("s_waitcnt vmcnt(0)" ::: "memory");
;       const unsigned og = xb_add(&bar[XB_TOP], 1u);
;       const unsigned tg = og / nx;
;       if (og + 1u == (tg + 1u) * nx) xb_add(&bar[XB_TOPGEN], 1u);
;       else XB_SPIN(xb_ld(&bar[XB_TOPGEN]) == tg, bar);
.LBB0_508:
	s_or_b64 exec, exec, s[2:3]
	v_cvt_f32_u32_e32 v5, v3
	s_waitcnt vmcnt(0)
	v_readfirstlane_b32 s2, v4
	v_sub_u32_e32 v4, 0, v3
	v_rcp_iflag_f32_e32 v5, v5
	v_add_u32_e32 v6, s2, v1
	v_mul_f32_e32 v5, 0x4f7ffffe, v5
	v_cvt_u32_f32_e32 v5, v5
	v_mul_lo_u32 v1, v4, v5
	v_mul_hi_u32 v1, v5, v1
	v_add_u32_e32 v1, v5, v1
	v_mul_hi_u32 v1, v6, v1
	v_mul_lo_u32 v4, v1, v3
	v_sub_u32_e32 v4, v6, v4
	v_add_u32_e32 v5, 1, v1
	v_cmp_ge_u32_e32 vcc, v4, v3
	s_nop 1
	v_cndmask_b32_e32 v1, v1, v5, vcc
	v_sub_u32_e32 v5, v4, v3
	v_cndmask_b32_e32 v4, v4, v5, vcc
	v_add_u32_e32 v5, 1, v1
	v_cmp_ge_u32_e32 vcc, v4, v3
	v_add_u32_e32 v4, 1, v6
	s_nop 0
	v_cndmask_b32_e32 v1, v1, v5, vcc
	v_mul_lo_u32 v5, v3, v1
	v_add_u32_e32 v3, v5, v3
	v_cmp_ne_u32_e32 vcc, v4, v3
	s_and_saveexec_b64 s[2:3], vcc
	s_xor_b64 s[2:3], exec, s[2:3]
	s_cbranch_execz .LBB0_522
	buffer_inv sc1
	v_readlane_b32 s4, v253, 21
	v_readlane_b32 s5, v253, 22
	s_waitcnt lgkmcnt(0)
	s_nop 3
	global_load_dword v0, v2, s[4:5] sc1
	s_waitcnt vmcnt(0)
	v_cmp_eq_u32_e32 vcc, v0, v1
	s_and_saveexec_b64 s[4:5], vcc
	s_cbranch_execz .LBB0_521
	s_mov_b32 s7, 1
	s_mov_b64 s[12:13], 0
	s_branch .LBB0_512

; DI unsigned xb_ld(unsigned* p) { return __hip_atomic_load(p, __ATOMIC_RELAXED, __HIP_MEMORY_SCOPE_AGENT); }
; DI unsigned xb_add(unsigned* p, unsigned v) { return __hip_atomic_fetch_add(p, v, __ATOMIC_RELAXED, __HIP_MEMORY_SCOPE_AGENT); }
; #define XB_SPIN(cond, bar) do { unsigned _sp = 0; while (cond) { __builtin_amdgcn_s_sleep(1); \
;     if ((++_sp & 255u) == 0u) { if (xb_ld(&(bar)[XB_TMO])) break; if (_sp > XB_SPIN_CAP) { atomicAdd(&(bar)[XB_TMO], 1u); break; } } } } while (0)
; DI void xcd_barrier(const XcdBarrier& b) {
;     ...
;       const unsigned og = xb_add(&bar[XB_TOP], 1u);
;       const unsigned tg = og / nx;
;       if (og + 1u == (tg + 1u) * nx) xb_add(&bar[XB_TOPGEN], 1u);
;       else XB_SPIN(xb_ld(&bar[XB_TOPGEN]) == tg, bar);
.LBB0_525:
	s_or_b64 exec, exec, s[4:5]
	buffer_inv sc1
	s_waitcnt vmcnt(0)
	v_readfirstlane_b32 s2, v3
	v_cvt_f32_u32_e32 v3, v0
	v_sub_u32_e32 v4, 0, v0
	v_add_u32_e32 v1, s2, v1
	v_readlane_b32 s2, v253, 25
	v_rcp_iflag_f32_e32 v3, v3
	v_readlane_b32 s3, v253, 26
	s_mov_b64 s[4:5], -1
	v_mul_f32_e32 v3, 0x4f7ffffe, v3
	v_cvt_u32_f32_e32 v3, v3
	v_mul_lo_u32 v4, v4, v3
	v_mul_hi_u32 v4, v3, v4
	v_add_u32_e32 v3, v3, v4
	v_mul_hi_u32 v3, v1, v3
	v_mul_lo_u32 v4, v3, v0
	v_sub_u32_e32 v4, v1, v4
	v_cmp_ge_u32_e32 vcc, v4, v0
	v_add_u32_e32 v5, 1, v3
	v_add_u32_e32 v1, 1, v1
	v_cndmask_b32_e32 v3, v3, v5, vcc
	v_sub_u32_e32 v5, v4, v0
	v_cndmask_b32_e32 v4, v4, v5, vcc
	v_cmp_ge_u32_e32 vcc, v4, v0
	v_add_u32_e32 v4, 1, v3
	s_nop 0
	v_cndmask_b32_e32 v3, v3, v4, vcc
	v_mul_lo_u32 v4, v0, v3
	v_add_u32_e32 v0, v4, v0
	v_cmp_ne_u32_e32 vcc, v1, v0
	v_mov_b64_e32 v[0:1], s[2:3]
	s_and_saveexec_b64 s[2:3], vcc
	s_cbranch_execz .LBB0_537
	v_readlane_b32 s4, v253, 25
	v_readlane_b32 s5, v253, 26
	s_mov_b64 s[12:13], 0
	s_nop 3
	global_load_dword v0, v2, s[4:5] sc1
	s_waitcnt vmcnt(0)
	v_cmp_eq_u32_e32 vcc, v0, v3
	s_and_saveexec_b64 s[4:5], vcc
	s_cbranch_execz .LBB0_536
	s_mov_b32 s7, 1
	s_branch .LBB0_529

; DI unsigned xb_ld(unsigned* p) { return __hip_atomic_load(p, __ATOMIC_RELAXED, __HIP_MEMORY_SCOPE_AGENT); }
; DI unsigned xb_add(unsigned* p, unsigned v) { return __hip_atomic_fetch_add(p, v, __ATOMIC_RELAXED, __HIP_MEMORY_SCOPE_AGENT); }
; #define XB_SPIN(cond, bar) do { unsigned _sp = 0; while (cond) { __builtin_amdgcn_s_sleep(1); \
;     if ((++_sp & 255u) == 0u) { if (xb_ld(&(bar)[XB_TMO])) break; if (_sp > XB_SPIN_CAP) { atomicAdd(&(bar)[XB_TMO], 1u); break; } } } } while (0)
; DI void xcd_barrier(const XcdBarrier& b) {
;     ...
;     const unsigned old = xb_add(&bar[XB_XSUB(b.x)], 1u);
;     const unsigned gen = old / nloc;
;     if (old + 1u == (gen + 1u) * nloc) {
;       __builtin_amdgcn_fence(__ATOMIC_RELEASE, "agent");
;       asm volatile("s_waitcnt vmcnt(0)" ::: "memory");
;       const unsigned og = xb_add(&bar[XB_TOP], 1u);
;       const unsigned tg = og / nx;
;       if (og + 1u == (tg + 1u) * nx) xb_add(&bar[XB_TOPGEN], 1u);
;       else XB_SPIN(xb_ld(&bar[XB_TOPGEN]) == tg, bar);
.LBB0_596:
	s_or_b64 exec, exec, s[2:3]
	v_cvt_f32_u32_e32 v5, v3
	s_waitcnt vmcnt(0)
	v_readfirstlane_b32 s2, v4
	v_sub_u32_e32 v4, 0, v3
	v_rcp_iflag_f32_e32 v5, v5
	v_add_u32_e32 v6, s2, v1
	v_mul_f32_e32 v5, 0x4f7ffffe, v5
	v_cvt_u32_f32_e32 v5, v5
	v_mul_lo_u32 v1, v4, v5
	v_mul_hi_u32 v1, v5, v1
	v_add_u32_e32 v1, v5, v1
	v_mul_hi_u32 v1, v6, v1
	v_mul_lo_u32 v4, v1, v3
	v_sub_u32_e32 v4, v6, v4
	v_add_u32_e32 v5, 1, v1
	v_cmp_ge_u32_e32 vcc, v4, v3
	s_nop 1
	v_cndmask_b32_e32 v1, v1, v5, vcc
	v_sub_u32_e32 v5, v4, v3
	v_cndmask_b32_e32 v4, v4, v5, vcc
	v_add_u32_e32 v5, 1, v1
	v_cmp_ge_u32_e32 vcc, v4, v3
	v_add_u32_e32 v4, 1, v6
	s_nop 0
	v_cndmask_b32_e32 v1, v1, v5, vcc
	v_mul_lo_u32 v5, v3, v1
	v_add_u32_e32 v3, v5, v3
	v_cmp_ne_u32_e32 vcc, v4, v3
	s_and_saveexec_b64 s[2:3], vcc
	s_xor_b64 s[2:3], exec, s[2:3]
	s_cbranch_execz .LBB0_610
	buffer_inv sc1
	v_readlane_b32 s4, v253, 21
	v_readlane_b32 s5, v253, 22
	s_waitcnt lgkmcnt(0)
	s_nop 3
	global_load_dword v0, v2, s[4:5] sc1
	s_waitcnt vmcnt(0)
	v_cmp_eq_u32_e32 vcc, v0, v1
	s_and_saveexec_b64 s[4:5], vcc
	s_cbranch_execz .LBB0_609
	s_mov_b32 s7, 1
	s_mov_b64 s[8:9], 0
	s_branch .LBB0_600

; DI unsigned xb_ld(unsigned* p) { return __hip_atomic_load(p, __ATOMIC_RELAXED, __HIP_MEMORY_SCOPE_AGENT); }
; DI unsigned xb_add(unsigned* p, unsigned v) { return __hip_atomic_fetch_add(p, v, __ATOMIC_RELAXED, __HIP_MEMORY_SCOPE_AGENT); }
; #define XB_SPIN(cond, bar) do { unsigned _sp = 0; while (cond) { __builtin_amdgcn_s_sleep(1); \
;     if ((++_sp & 255u) == 0u) { if (xb_ld(&(bar)[XB_TMO])) break; if (_sp > XB_SPIN_CAP) { atomicAdd(&(bar)[XB_TMO], 1u); break; } } } } while (0)
; DI void xcd_barrier(const XcdBarrier& b) {
;     ...
;       const unsigned og = xb_add(&bar[XB_TOP], 1u);
;       const unsigned tg = og / nx;
;       if (og + 1u == (tg + 1u) * nx) xb_add(&bar[XB_TOPGEN], 1u);
;       else XB_SPIN(xb_ld(&bar[XB_TOPGEN]) == tg, bar);
.LBB0_613:
	s_or_b64 exec, exec, s[4:5]
	buffer_inv sc1
	s_waitcnt vmcnt(0)
	v_readfirstlane_b32 s2, v3
	v_cvt_f32_u32_e32 v3, v0
	v_sub_u32_e32 v4, 0, v0
	v_add_u32_e32 v1, s2, v1
	v_readlane_b32 s2, v253, 25
	v_rcp_iflag_f32_e32 v3, v3
	v_readlane_b32 s3, v253, 26
	s_mov_b64 s[4:5], -1
	v_mul_f32_e32 v3, 0x4f7ffffe, v3
	v_cvt_u32_f32_e32 v3, v3
	v_mul_lo_u32 v4, v4, v3
	v_mul_hi_u32 v4, v3, v4
	v_add_u32_e32 v3, v3, v4
	v_mul_hi_u32 v3, v1, v3
	v_mul_lo_u32 v4, v3, v0
	v_sub_u32_e32 v4, v1, v4
	v_cmp_ge_u32_e32 vcc, v4, v0
	v_add_u32_e32 v5, 1, v3
	v_add_u32_e32 v1, 1, v1
	v_cndmask_b32_e32 v3, v3, v5, vcc
	v_sub_u32_e32 v5, v4, v0
	v_cndmask_b32_e32 v4, v4, v5, vcc
	v_cmp_ge_u32_e32 vcc, v4, v0
	v_add_u32_e32 v4, 1, v3
	s_nop 0
	v_cndmask_b32_e32 v3, v3, v4, vcc
	v_mul_lo_u32 v4, v0, v3
	v_add_u32_e32 v0, v4, v0
	v_cmp_ne_u32_e32 vcc, v1, v0
	v_mov_b64_e32 v[0:1], s[2:3]
	s_and_saveexec_b64 s[2:3], vcc
	s_cbranch_execz .LBB0_625
	v_readlane_b32 s4, v253, 25
	v_readlane_b32 s5, v253, 26
	s_mov_b64 s[8:9], 0
	s_nop 3
	global_load_dword v0, v2, s[4:5] sc1
	s_waitcnt vmcnt(0)
	v_cmp_eq_u32_e32 vcc, v0, v3
	s_and_saveexec_b64 s[4:5], vcc
	s_cbranch_execz .LBB0_624
	s_mov_b32 s7, 1
	s_branch .LBB0_617

; DI unsigned xb_ld(unsigned* p) { return __hip_atomic_load(p, __ATOMIC_RELAXED, __HIP_MEMORY_SCOPE_AGENT); }
; DI unsigned xb_add(unsigned* p, unsigned v) { return __hip_atomic_fetch_add(p, v, __ATOMIC_RELAXED, __HIP_MEMORY_SCOPE_AGENT); }
; #define XB_SPIN(cond, bar) do { unsigned _sp = 0; while (cond) { __builtin_amdgcn_s_sleep(1); \
;     if ((++_sp & 255u) == 0u) { if (xb_ld(&(bar)[XB_TMO])) break; if (_sp > XB_SPIN_CAP) { atomicAdd(&(bar)[XB_TMO], 1u); break; } } } } while (0)
; DI void xcd_barrier(const XcdBarrier& b) {
;     ...
;     const unsigned old = xb_add(&bar[XB_XSUB(b.x)], 1u);
;     const unsigned gen = old / nloc;
;     if (old + 1u == (gen + 1u) * nloc) {
;       __builtin_amdgcn_fence(__ATOMIC_RELEASE, "agent");
;       asm volatile("s_waitcnt vmcnt(0)" ::: "memory");
;       const unsigned og = xb_add(&bar[XB_TOP], 1u);
;       const unsigned tg = og / nx;
;       if (og + 1u == (tg + 1u) * nx) xb_add(&bar[XB_TOPGEN], 1u);
;       else XB_SPIN(xb_ld(&bar[XB_TOPGEN]) == tg, bar);
.LBB0_868:
	s_or_b64 exec, exec, s[2:3]
	v_cvt_f32_u32_e32 v5, v3
	s_waitcnt vmcnt(0)
	v_readfirstlane_b32 s2, v4
	v_sub_u32_e32 v4, 0, v3
	v_rcp_iflag_f32_e32 v5, v5
	v_add_u32_e32 v6, s2, v1
	v_mul_f32_e32 v5, 0x4f7ffffe, v5
	v_cvt_u32_f32_e32 v5, v5
	v_mul_lo_u32 v1, v4, v5
	v_mul_hi_u32 v1, v5, v1
	v_add_u32_e32 v1, v5, v1
	v_mul_hi_u32 v1, v6, v1
	v_mul_lo_u32 v4, v1, v3
	v_sub_u32_e32 v4, v6, v4
	v_add_u32_e32 v5, 1, v1
	v_cmp_ge_u32_e32 vcc, v4, v3
	s_nop 1
	v_cndmask_b32_e32 v1, v1, v5, vcc
	v_sub_u32_e32 v5, v4, v3
	v_cndmask_b32_e32 v4, v4, v5, vcc
	v_add_u32_e32 v5, 1, v1
	v_cmp_ge_u32_e32 vcc, v4, v3
	v_add_u32_e32 v4, 1, v6
	s_nop 0
	v_cndmask_b32_e32 v1, v1, v5, vcc
	v_mul_lo_u32 v5, v3, v1
	v_add_u32_e32 v3, v5, v3
	v_cmp_ne_u32_e32 vcc, v4, v3
	s_and_saveexec_b64 s[2:3], vcc
	s_xor_b64 s[2:3], exec, s[2:3]
	s_cbranch_execz .LBB0_882
	buffer_inv sc1
	v_readlane_b32 s4, v253, 21
	v_readlane_b32 s5, v253, 22
	s_waitcnt lgkmcnt(0)
	s_nop 3
	global_load_dword v0, v2, s[4:5] sc1
	s_waitcnt vmcnt(0)
	v_cmp_eq_u32_e32 vcc, v0, v1
	s_and_saveexec_b64 s[4:5], vcc
	s_cbranch_execz .LBB0_881
	s_mov_b32 s24, 1
	s_mov_b64 s[6:7], 0
	s_branch .LBB0_872

; DI unsigned xb_ld(unsigned* p) { return __hip_atomic_load(p, __ATOMIC_RELAXED, __HIP_MEMORY_SCOPE_AGENT); }
; DI unsigned xb_add(unsigned* p, unsigned v) { return __hip_atomic_fetch_add(p, v, __ATOMIC_RELAXED, __HIP_MEMORY_SCOPE_AGENT); }
; #define XB_SPIN(cond, bar) do { unsigned _sp = 0; while (cond) { __builtin_amdgcn_s_sleep(1); \
;     if ((++_sp & 255u) == 0u) { if (xb_ld(&(bar)[XB_TMO])) break; if (_sp > XB_SPIN_CAP) { atomicAdd(&(bar)[XB_TMO], 1u); break; } } } } while (0)
; DI void xcd_barrier(const XcdBarrier& b) {
;     ...
;       const unsigned og = xb_add(&bar[XB_TOP], 1u);
;       const unsigned tg = og / nx;
;       if (og + 1u == (tg + 1u) * nx) xb_add(&bar[XB_TOPGEN], 1u);
;       else XB_SPIN(xb_ld(&bar[XB_TOPGEN]) == tg, bar);
.LBB0_885:
	s_or_b64 exec, exec, s[4:5]
	buffer_inv sc1
	s_waitcnt vmcnt(0)
	v_readfirstlane_b32 s2, v3
	v_cvt_f32_u32_e32 v3, v0
	v_sub_u32_e32 v4, 0, v0
	v_add_u32_e32 v1, s2, v1
	v_readlane_b32 s2, v253, 25
	v_rcp_iflag_f32_e32 v3, v3
	v_readlane_b32 s3, v253, 26
	s_mov_b64 s[4:5], -1
	v_mul_f32_e32 v3, 0x4f7ffffe, v3
	v_cvt_u32_f32_e32 v3, v3
	v_mul_lo_u32 v4, v4, v3
	v_mul_hi_u32 v4, v3, v4
	v_add_u32_e32 v3, v3, v4
	v_mul_hi_u32 v3, v1, v3
	v_mul_lo_u32 v4, v3, v0
	v_sub_u32_e32 v4, v1, v4
	v_cmp_ge_u32_e32 vcc, v4, v0
	v_add_u32_e32 v5, 1, v3
	v_add_u32_e32 v1, 1, v1
	v_cndmask_b32_e32 v3, v3, v5, vcc
	v_sub_u32_e32 v5, v4, v0
	v_cndmask_b32_e32 v4, v4, v5, vcc
	v_cmp_ge_u32_e32 vcc, v4, v0
	v_add_u32_e32 v4, 1, v3
	s_nop 0
	v_cndmask_b32_e32 v3, v3, v4, vcc
	v_mul_lo_u32 v4, v0, v3
	v_add_u32_e32 v0, v4, v0
	v_cmp_ne_u32_e32 vcc, v1, v0
	v_mov_b64_e32 v[0:1], s[2:3]
	s_and_saveexec_b64 s[2:3], vcc
	s_cbranch_execz .LBB0_897
	v_readlane_b32 s4, v253, 25
	v_readlane_b32 s5, v253, 26
	s_mov_b64 s[6:7], 0
	s_nop 3
	global_load_dword v0, v2, s[4:5] sc1
	s_waitcnt vmcnt(0)
	v_cmp_eq_u32_e32 vcc, v0, v3
	s_and_saveexec_b64 s[4:5], vcc
	s_cbranch_execz .LBB0_896
	s_mov_b32 s24, 1
	s_branch .LBB0_889
